# GEMM k-loops: +0x100 folded into the scalar k offset (6 fewer 64-bit VALU adds before the barrier)
# speedup vs baseline: 1.1318x; 1.0076x over previous
; __device__ __forceinline__ void lds_barrier() { asm volatile("s_waitcnt lgkmcnt(0)\n\ts_barrier" ::: "memory"); }
; template <int EPI>
; __device__ void gemm_phase(const u16* __restrict__ A, const u16* __restrict__ Bt, void* __restrict__ Cv,
;                            int N, int K, int ldc, unsigned char* ldsraw, int G) {
;     ...
;     GLDS(0, 0);
;     GLDS(1, 1);
;     if (__builtin_amdgcn_readfirstlane(tid) >= 256) __builtin_amdgcn_s_setprio(1);
;     int st = 0;
;     for (int kt = 0; kt < nk; ++kt) {
;       asm volatile("s_waitcnt vmcnt(6)" ::: "memory");
;       lds_barrier();
;       const int st2 = (st >= 1) ? st - 1 : 2;
;       GLDS(st2, kt + 2);
;       const u16* Asx = As + st * STG;
;       const u16* Bsx = Asx + GBM * GLD;
; #pragma unroll
;       for (int ks = 0; ks < 2; ++ks) {
;         const int fsw = ((ks * 4 + g4) ^ fx) * 8;
;         bf16x8 bfr[4];
; #pragma unroll
;         for (int jx = 0; jx < 4; ++jx) bfr[jx] = *(const bf16x8*)(Bsx + (wn * 64 + jx * 16 + l15) * GLD + fsw);
; #pragma unroll
;         for (int ix = 0; ix < 4; ++ix) {
;           const bf16x8 af = *(const bf16x8*)(Asx + (wm * 64 + ix * 16 + l15) * GLD + fsw);
; #pragma unroll
;           for (int jx = 0; jx < 4; ++jx)
;             acc[ix][jx] = __builtin_amdgcn_mfma_f32_16x16x32_bf16(af, bfr[jx], acc[ix][jx], 0, 0, 0);
;         }
;       }
;       st = (st == 2) ? 0 : st + 1;
;     }
.LBB0_20:
	s_mul_i32 s8, s5, 0xc000
	s_min_u32 s7, s6, 61
	s_add_i32 s9, s8, 0xffff4000
	s_cmp_gt_i32 s5, 0
	s_waitcnt vmcnt(6)
	s_cselect_b32 s9, s9, 0x18000
	s_lshl_b32 s98, s7, 7
	s_add_i32 s98, s98, 0x100
	s_add_i32 s7, s8, 0x100
	s_add_i32 s8, s9, s4
	s_add_i32 s9, s8, 0x2000
	s_add_i32 s11, s8, 0x4000
	s_add_i32 s12, s8, 0x6000
	s_add_i32 s13, s8, 0x8000
	s_add_i32 s14, s8, 0xa000
	v_lshl_add_u64 v[236:237], v[76:77], 0, s[98:99]
	v_lshl_add_u64 v[238:239], v[80:81], 0, s[98:99]
	v_lshl_add_u64 v[240:241], v[82:83], 0, s[98:99]
	v_lshl_add_u64 v[242:243], v[84:85], 0, s[98:99]
	v_lshl_add_u64 v[244:245], v[78:79], 0, s[98:99]
	v_lshl_add_u64 v[246:247], v[86:87], 0, s[98:99]
	v_lshl_add_u32 v109, v104, 1, s7
	v_add3_u32 v130, v109, v105, v106
	v_add3_u32 v109, v109, v107, v106
	s_waitcnt lgkmcnt(0)
	s_barrier
	s_mov_b32 s15, m0
	ds_read_b128 v[110:113], v109
	ds_read_b128 v[114:117], v130 offset:32768
	ds_read_b128 v[118:121], v130 offset:34816
	ds_read_b128 v[122:125], v109 offset:2048
	ds_read_b128 v[126:129], v130 offset:36864
	ds_read_b128 v[130:133], v130 offset:38912
	s_waitcnt lgkmcnt(4)
	v_mfma_f32_16x16x32_bf16 v[64:67], v[110:113], v[114:117], v[64:67]
	s_waitcnt lgkmcnt(3)
	v_mfma_f32_16x16x32_bf16 v[60:63], v[110:113], v[118:121], v[60:63]
	s_waitcnt lgkmcnt(1)
	v_mfma_f32_16x16x32_bf16 v[56:59], v[110:113], v[126:129], v[56:59]
	s_waitcnt lgkmcnt(0)
	s_mov_b32 m0, s8
	v_mfma_f32_16x16x32_bf16 v[52:55], v[110:113], v[130:133], v[52:55]
	global_load_lds_dwordx4 v[236:237], off
	v_mfma_f32_16x16x32_bf16 v[48:51], v[122:125], v[114:117], v[48:51]
	v_mfma_f32_16x16x32_bf16 v[44:47], v[122:125], v[118:121], v[44:47]
	v_mfma_f32_16x16x32_bf16 v[40:43], v[122:125], v[126:129], v[40:43]
	v_mfma_f32_16x16x32_bf16 v[36:39], v[122:125], v[130:133], v[36:39]
	ds_read_b128 v[110:113], v109 offset:4096
	ds_read_b128 v[122:125], v109 offset:6144
	v_lshl_add_u32 v109, v108, 1, s7
	v_add3_u32 v134, v109, v105, v106
	v_add3_u32 v109, v109, v107, v106
	s_waitcnt lgkmcnt(1)
	s_mov_b32 m0, s9
	v_mfma_f32_16x16x32_bf16 v[32:35], v[110:113], v[114:117], v[32:35]
	global_load_lds_dwordx4 v[238:239], off
	s_add_i32 s7, s5, 1
	s_cmp_lg_u32 s5, 2
	s_cselect_b32 s5, s7, 0
	v_mfma_f32_16x16x32_bf16 v[28:31], v[110:113], v[118:121], v[28:31]
	s_add_i32 s6, s6, 1
	s_cmp_eq_u32 s6, 64
	v_mfma_f32_16x16x32_bf16 v[24:27], v[110:113], v[126:129], v[24:27]
	v_mfma_f32_16x16x32_bf16 v[20:23], v[110:113], v[130:133], v[20:23]
	ds_read_b128 v[110:113], v109
	s_waitcnt lgkmcnt(1)
	v_mfma_f32_16x16x32_bf16 v[16:19], v[122:125], v[114:117], v[16:19]
	s_mov_b32 m0, s11
	v_mfma_f32_16x16x32_bf16 v[12:15], v[122:125], v[118:121], v[12:15]
	global_load_lds_dwordx4 v[240:241], off
	v_mfma_f32_16x16x32_bf16 v[8:11], v[122:125], v[126:129], v[8:11]
	v_mfma_f32_16x16x32_bf16 v[2:5], v[122:125], v[130:133], v[2:5]
	ds_read_b128 v[114:117], v134 offset:32768
	ds_read_b128 v[118:121], v134 offset:34816
	ds_read_b128 v[122:125], v109 offset:2048
	ds_read_b128 v[126:129], v134 offset:36864
	ds_read_b128 v[130:133], v134 offset:38912
	s_waitcnt lgkmcnt(4)
	v_mfma_f32_16x16x32_bf16 v[64:67], v[110:113], v[114:117], v[64:67]
	s_waitcnt lgkmcnt(3)
	v_mfma_f32_16x16x32_bf16 v[60:63], v[110:113], v[118:121], v[60:63]
	s_waitcnt lgkmcnt(1)
	s_mov_b32 m0, s12
	v_mfma_f32_16x16x32_bf16 v[56:59], v[110:113], v[126:129], v[56:59]
	global_load_lds_dwordx4 v[242:243], off
	s_waitcnt lgkmcnt(0)
	v_mfma_f32_16x16x32_bf16 v[52:55], v[110:113], v[130:133], v[52:55]
	v_mfma_f32_16x16x32_bf16 v[48:51], v[122:125], v[114:117], v[48:51]
	v_mfma_f32_16x16x32_bf16 v[44:47], v[122:125], v[118:121], v[44:47]
	v_mfma_f32_16x16x32_bf16 v[40:43], v[122:125], v[126:129], v[40:43]
	s_mov_b32 m0, s13
	v_mfma_f32_16x16x32_bf16 v[36:39], v[122:125], v[130:133], v[36:39]
	global_load_lds_dwordx4 v[244:245], off
	ds_read_b128 v[110:113], v109 offset:4096
	ds_read_b128 v[122:125], v109 offset:6144
	s_waitcnt lgkmcnt(1)
	v_mfma_f32_16x16x32_bf16 v[32:35], v[110:113], v[114:117], v[32:35]
	v_mfma_f32_16x16x32_bf16 v[28:31], v[110:113], v[118:121], v[28:31]
	v_mfma_f32_16x16x32_bf16 v[24:27], v[110:113], v[126:129], v[24:27]
	v_mfma_f32_16x16x32_bf16 v[20:23], v[110:113], v[130:133], v[20:23]
	s_waitcnt lgkmcnt(0)
	s_mov_b32 m0, s14
	v_mfma_f32_16x16x32_bf16 v[16:19], v[122:125], v[114:117], v[16:19]
	global_load_lds_dwordx4 v[246:247], off
	s_mov_b32 m0, s15
	v_mfma_f32_16x16x32_bf16 v[12:15], v[122:125], v[118:121], v[12:15]
	v_mfma_f32_16x16x32_bf16 v[8:11], v[122:125], v[126:129], v[8:11]
	v_mfma_f32_16x16x32_bf16 v[2:5], v[122:125], v[130:133], v[2:5]
	s_cbranch_scc0 .LBB0_20
	s_setprio 0
	s_waitcnt vmcnt(0)
	v_add_u32_e32 v78, s0, v0
	v_or_b32_e32 v82, s1, v75
	s_waitcnt lgkmcnt(0)
	s_barrier
	v_ashrrev_i32_e32 v83, 31, v82
	v_ashrrev_i32_e32 v79, 31, v78
	v_lshl_add_u64 v[76:77], v[82:83], 1, s[76:77]
	v_lshlrev_b64 v[80:81], 11, v[78:79]
	s_movk_i32 s0, 0x400
	v_lshl_add_u64 v[80:81], v[76:77], 0, v[80:81]
	v_cmp_gt_i32_e32 vcc, s0, v82
	s_and_saveexec_b64 s[0:1], vcc
	s_cbranch_execz .LBB0_23
	v_bfe_u32 v79, v64, 16, 1
	v_add3_u32 v64, v64, v79, s96
	global_store_short_d16_hi v[80:81], v64, off

; __device__ __forceinline__ void lds_barrier() { asm volatile("s_waitcnt lgkmcnt(0)\n\ts_barrier" ::: "memory"); }
; template <int EPI>
; __device__ void gemm_phase(const u16* __restrict__ A, const u16* __restrict__ Bt, void* __restrict__ Cv,
;                            int N, int K, int ldc, unsigned char* ldsraw, int G) {
;     ...
;     GLDS(0, 0);
;     GLDS(1, 1);
;     if (__builtin_amdgcn_readfirstlane(tid) >= 256) __builtin_amdgcn_s_setprio(1);
;     int st = 0;
;     for (int kt = 0; kt < nk; ++kt) {
;       asm volatile("s_waitcnt vmcnt(6)" ::: "memory");
;       lds_barrier();
;       const int st2 = (st >= 1) ? st - 1 : 2;
;       GLDS(st2, kt + 2);
;       const u16* Asx = As + st * STG;
;       const u16* Bsx = Asx + GBM * GLD;
; #pragma unroll
;       for (int ks = 0; ks < 2; ++ks) {
;         const int fsw = ((ks * 4 + g4) ^ fx) * 8;
;         bf16x8 bfr[4];
; #pragma unroll
;         for (int jx = 0; jx < 4; ++jx) bfr[jx] = *(const bf16x8*)(Bsx + (wn * 64 + jx * 16 + l15) * GLD + fsw);
; #pragma unroll
;         for (int ix = 0; ix < 4; ++ix) {
;           const bf16x8 af = *(const bf16x8*)(Asx + (wm * 64 + ix * 16 + l15) * GLD + fsw);
; #pragma unroll
;           for (int jx = 0; jx < 4; ++jx)
;             acc[ix][jx] = __builtin_amdgcn_mfma_f32_16x16x32_bf16(af, bfr[jx], acc[ix][jx], 0, 0, 0);
;         }
;       }
;       st = (st == 2) ? 0 : st + 1;
;     }
.LBB0_157:
	s_mul_i32 s9, s6, 0xc000
	s_min_u32 s8, s7, 13
	s_add_i32 s10, s9, 0xffff4000
	s_cmp_gt_i32 s6, 0
	s_waitcnt vmcnt(6)
	s_cselect_b32 s10, s10, 0x18000
	s_lshl_b32 s98, s8, 7
	s_add_i32 s98, s98, 0x100
	s_add_i32 s8, s9, 0x100
	s_add_i32 s9, s10, s5
	s_add_i32 s10, s9, 0x2000
	s_add_i32 s11, s9, 0x4000
	s_add_i32 s12, s9, 0x6000
	s_add_i32 s13, s9, 0x8000
	s_add_i32 s14, s9, 0xa000
	v_lshl_add_u64 v[236:237], v[76:77], 0, s[98:99]
	v_lshl_add_u64 v[238:239], v[80:81], 0, s[98:99]
	v_lshl_add_u64 v[240:241], v[82:83], 0, s[98:99]
	v_lshl_add_u64 v[242:243], v[84:85], 0, s[98:99]
	v_lshl_add_u64 v[244:245], v[78:79], 0, s[98:99]
	v_lshl_add_u64 v[246:247], v[86:87], 0, s[98:99]
	v_lshl_add_u32 v109, v104, 1, s8
	v_add3_u32 v130, v109, v105, v106
	v_add3_u32 v109, v109, v107, v106
	s_waitcnt lgkmcnt(0)
	s_barrier
	s_mov_b32 s15, m0
	ds_read_b128 v[110:113], v109
	ds_read_b128 v[114:117], v130 offset:32768
	ds_read_b128 v[118:121], v130 offset:34816
	ds_read_b128 v[122:125], v109 offset:2048
	ds_read_b128 v[126:129], v130 offset:36864
	ds_read_b128 v[130:133], v130 offset:38912
	s_waitcnt lgkmcnt(4)
	v_mfma_f32_16x16x32_bf16 v[64:67], v[110:113], v[114:117], v[64:67]
	s_waitcnt lgkmcnt(3)
	v_mfma_f32_16x16x32_bf16 v[60:63], v[110:113], v[118:121], v[60:63]
	s_waitcnt lgkmcnt(1)
	v_mfma_f32_16x16x32_bf16 v[56:59], v[110:113], v[126:129], v[56:59]
	s_waitcnt lgkmcnt(0)
	s_mov_b32 m0, s9
	v_mfma_f32_16x16x32_bf16 v[52:55], v[110:113], v[130:133], v[52:55]
	global_load_lds_dwordx4 v[236:237], off
	v_mfma_f32_16x16x32_bf16 v[48:51], v[122:125], v[114:117], v[48:51]
	v_mfma_f32_16x16x32_bf16 v[44:47], v[122:125], v[118:121], v[44:47]
	v_mfma_f32_16x16x32_bf16 v[40:43], v[122:125], v[126:129], v[40:43]
	v_mfma_f32_16x16x32_bf16 v[36:39], v[122:125], v[130:133], v[36:39]
	ds_read_b128 v[110:113], v109 offset:4096
	ds_read_b128 v[122:125], v109 offset:6144
	v_lshl_add_u32 v109, v108, 1, s8
	v_add3_u32 v134, v109, v105, v106
	v_add3_u32 v109, v109, v107, v106
	s_waitcnt lgkmcnt(1)
	s_mov_b32 m0, s10
	v_mfma_f32_16x16x32_bf16 v[32:35], v[110:113], v[114:117], v[32:35]
	global_load_lds_dwordx4 v[238:239], off
	s_add_i32 s8, s6, 1
	s_cmp_lg_u32 s6, 2
	s_cselect_b32 s6, s8, 0
	v_mfma_f32_16x16x32_bf16 v[28:31], v[110:113], v[118:121], v[28:31]
	s_add_i32 s7, s7, 1
	s_cmp_eq_u32 s7, 16
	v_mfma_f32_16x16x32_bf16 v[24:27], v[110:113], v[126:129], v[24:27]
	v_mfma_f32_16x16x32_bf16 v[20:23], v[110:113], v[130:133], v[20:23]
	ds_read_b128 v[110:113], v109
	s_waitcnt lgkmcnt(1)
	v_mfma_f32_16x16x32_bf16 v[16:19], v[122:125], v[114:117], v[16:19]
	s_mov_b32 m0, s11
	v_mfma_f32_16x16x32_bf16 v[12:15], v[122:125], v[118:121], v[12:15]
	global_load_lds_dwordx4 v[240:241], off
	v_mfma_f32_16x16x32_bf16 v[8:11], v[122:125], v[126:129], v[8:11]
	v_mfma_f32_16x16x32_bf16 v[2:5], v[122:125], v[130:133], v[2:5]
	ds_read_b128 v[114:117], v134 offset:32768
	ds_read_b128 v[118:121], v134 offset:34816
	ds_read_b128 v[122:125], v109 offset:2048
	ds_read_b128 v[126:129], v134 offset:36864
	ds_read_b128 v[130:133], v134 offset:38912
	s_waitcnt lgkmcnt(4)
	v_mfma_f32_16x16x32_bf16 v[64:67], v[110:113], v[114:117], v[64:67]
	s_waitcnt lgkmcnt(3)
	v_mfma_f32_16x16x32_bf16 v[60:63], v[110:113], v[118:121], v[60:63]
	s_waitcnt lgkmcnt(1)
	s_mov_b32 m0, s12
	v_mfma_f32_16x16x32_bf16 v[56:59], v[110:113], v[126:129], v[56:59]
	global_load_lds_dwordx4 v[242:243], off
	s_waitcnt lgkmcnt(0)
	v_mfma_f32_16x16x32_bf16 v[52:55], v[110:113], v[130:133], v[52:55]
	v_mfma_f32_16x16x32_bf16 v[48:51], v[122:125], v[114:117], v[48:51]
	v_mfma_f32_16x16x32_bf16 v[44:47], v[122:125], v[118:121], v[44:47]
	v_mfma_f32_16x16x32_bf16 v[40:43], v[122:125], v[126:129], v[40:43]
	s_mov_b32 m0, s13
	v_mfma_f32_16x16x32_bf16 v[36:39], v[122:125], v[130:133], v[36:39]
	global_load_lds_dwordx4 v[244:245], off
	ds_read_b128 v[110:113], v109 offset:4096
	ds_read_b128 v[122:125], v109 offset:6144
	s_waitcnt lgkmcnt(1)
	v_mfma_f32_16x16x32_bf16 v[32:35], v[110:113], v[114:117], v[32:35]
	v_mfma_f32_16x16x32_bf16 v[28:31], v[110:113], v[118:121], v[28:31]
	v_mfma_f32_16x16x32_bf16 v[24:27], v[110:113], v[126:129], v[24:27]
	v_mfma_f32_16x16x32_bf16 v[20:23], v[110:113], v[130:133], v[20:23]
	s_waitcnt lgkmcnt(0)
	s_mov_b32 m0, s14
	v_mfma_f32_16x16x32_bf16 v[16:19], v[122:125], v[114:117], v[16:19]
	global_load_lds_dwordx4 v[246:247], off
	s_mov_b32 m0, s15
	v_mfma_f32_16x16x32_bf16 v[12:15], v[122:125], v[118:121], v[12:15]
	v_mfma_f32_16x16x32_bf16 v[8:11], v[122:125], v[126:129], v[8:11]
	v_mfma_f32_16x16x32_bf16 v[2:5], v[122:125], v[130:133], v[2:5]
	s_cbranch_scc0 .LBB0_157
	s_setprio 0
	v_max_f32_e32 v64, v64, v64
	v_add_u32_e32 v78, s1, v0
	v_or_b32_e32 v76, s4, v75
	v_max_f32_e32 v64, 0, v64
	v_ashrrev_i32_e32 v77, 31, v76
	v_ashrrev_i32_e32 v79, 31, v78
	v_mul_f32_e32 v64, v64, v64
	v_max_f32_e32 v60, v60, v60
	v_lshl_add_u64 v[76:77], v[76:77], 1, s[18:19]
	v_lshlrev_b64 v[80:81], 13, v[78:79]
	v_bfe_u32 v79, v64, 16, 1
	v_max_f32_e32 v60, 0, v60
	s_waitcnt vmcnt(0)
	v_lshl_add_u64 v[80:81], v[76:77], 0, v[80:81]
	v_add3_u32 v64, v64, v79, s96
	v_mul_f32_e32 v60, v60, v60
	v_max_f32_e32 v56, v56, v56
	s_waitcnt lgkmcnt(0)
	s_barrier
; template <int EPI>
; __device__ void gemm_phase(const u16* __restrict__ A, const u16* __restrict__ Bt, void* __restrict__ Cv,
;                            int N, int K, int ldc, unsigned char* ldsraw, int G) {
;     ...
;     for (int i = 0; i < 4; ++i) {
; #pragma unroll
;       for (int r = 0; r < 4; ++r) {
;         const int m = m0 + wm * 64 + i * 16 + g4 * 4 + r;
;         const int nb = n0 + wn * 64 + l15;
;         if (EPI == EPI_F32) {
;           float* cp = (float*)Cv + (size_t)m * ldc + nb;
; #pragma unroll
;           for (int j = 0; j < 4; ++j) if (nb + j * 16 < N) cp[j * 16] = acc[i][j][r];
;         } else {
;           u16* cp = (u16*)Cv + (size_t)m * ldc + nb;
; #pragma unroll
;           for (int j = 0; j < 4; ++j) {
;             float v = acc[i][j][r];
;             if (EPI == EPI_RELU2) { v = fmaxf(v, 0.f); v = v * v; }
;             if (nb + j * 16 < N) cp[j * 16] = f2bf(v);
;           }
	global_store_short_d16_hi v[80:81], v64, off
	v_bfe_u32 v64, v60, 16, 1
	v_max_f32_e32 v56, 0, v56
	v_add3_u32 v60, v60, v64, s96
	v_mul_f32_e32 v56, v56, v56
	v_max_f32_e32 v52, v52, v52
	global_store_short_d16_hi v[80:81], v60, off offset:32
	v_bfe_u32 v60, v56, 16, 1
	v_max_f32_e32 v52, 0, v52
	v_add3_u32 v56, v56, v60, s96
	v_mul_f32_e32 v52, v52, v52
	global_store_short_d16_hi v[80:81], v56, off offset:64
	v_bfe_u32 v56, v52, 16, 1
	v_add3_u32 v52, v52, v56, s96
	global_store_short_d16_hi v[80:81], v52, off offset:96
	v_max_f32_e32 v52, v65, v65
	v_or_b32_e32 v80, 1, v78
	v_max_f32_e32 v52, 0, v52
	v_ashrrev_i32_e32 v81, 31, v80
	v_mul_f32_e32 v52, v52, v52
	v_lshlrev_b64 v[80:81], 13, v[80:81]
	v_bfe_u32 v56, v52, 16, 1
	v_lshl_add_u64 v[80:81], v[76:77], 0, v[80:81]
	v_add3_u32 v52, v52, v56, s96
	global_store_short_d16_hi v[80:81], v52, off
	v_max_f32_e32 v52, v61, v61
	v_max_f32_e32 v52, 0, v52
	v_mul_f32_e32 v52, v52, v52
	v_bfe_u32 v56, v52, 16, 1
	v_add3_u32 v52, v52, v56, s96
	global_store_short_d16_hi v[80:81], v52, off offset:32
	v_max_f32_e32 v52, v57, v57
	v_max_f32_e32 v52, 0, v52
	v_mul_f32_e32 v52, v52, v52
	v_bfe_u32 v56, v52, 16, 1
	v_add3_u32 v52, v52, v56, s96
	global_store_short_d16_hi v[80:81], v52, off offset:64
	v_max_f32_e32 v52, v53, v53
	v_max_f32_e32 v52, 0, v52
	v_mul_f32_e32 v52, v52, v52
	v_bfe_u32 v53, v52, 16, 1
	v_add3_u32 v52, v52, v53, s96
	v_max_f32_e32 v56, v66, v66
	global_store_short_d16_hi v[80:81], v52, off offset:96
	v_or_b32_e32 v52, 2, v78
	v_max_f32_e32 v56, 0, v56
	v_ashrrev_i32_e32 v53, 31, v52
	v_mul_f32_e32 v56, v56, v56
	v_lshlrev_b64 v[52:53], 13, v[52:53]
	v_bfe_u32 v57, v56, 16, 1
	v_lshl_add_u64 v[52:53], v[76:77], 0, v[52:53]
	v_add3_u32 v56, v56, v57, s96
	global_store_short_d16_hi v[52:53], v56, off
	v_max_f32_e32 v56, v62, v62
	v_max_f32_e32 v56, 0, v56
	v_mul_f32_e32 v56, v56, v56
	v_bfe_u32 v57, v56, 16, 1
	v_add3_u32 v56, v56, v57, s96
	global_store_short_d16_hi v[52:53], v56, off offset:32
	v_max_f32_e32 v56, v58, v58
	v_max_f32_e32 v56, 0, v56
	v_mul_f32_e32 v56, v56, v56
	v_max_f32_e32 v54, v54, v54
	v_bfe_u32 v57, v56, 16, 1
	v_max_f32_e32 v54, 0, v54
	v_add3_u32 v56, v56, v57, s96
	v_mul_f32_e32 v54, v54, v54
	global_store_short_d16_hi v[52:53], v56, off offset:64
	v_bfe_u32 v56, v54, 16, 1
	v_add3_u32 v54, v54, v56, s96
	global_store_short_d16_hi v[52:53], v54, off offset:96
	v_max_f32_e32 v54, v67, v67
	v_or_b32_e32 v52, 3, v78
	v_max_f32_e32 v54, 0, v54
	v_ashrrev_i32_e32 v53, 31, v52
	v_mul_f32_e32 v54, v54, v54
	v_lshlrev_b64 v[52:53], 13, v[52:53]
	v_bfe_u32 v56, v54, 16, 1
	v_lshl_add_u64 v[52:53], v[76:77], 0, v[52:53]
	v_add3_u32 v54, v54, v56, s96
	global_store_short_d16_hi v[52:53], v54, off
	v_max_f32_e32 v54, v63, v63
	v_max_f32_e32 v54, 0, v54
	v_mul_f32_e32 v54, v54, v54
	v_bfe_u32 v56, v54, 16, 1
	v_add3_u32 v54, v54, v56, s96
	global_store_short_d16_hi v[52:53], v54, off offset:32
	v_max_f32_e32 v54, v59, v59
	v_max_f32_e32 v54, 0, v54
	v_mul_f32_e32 v54, v54, v54
	v_bfe_u32 v56, v54, 16, 1
	v_add3_u32 v54, v54, v56, s96
	global_store_short_d16_hi v[52:53], v54, off offset:64
	v_max_f32_e32 v54, v55, v55
	v_max_f32_e32 v54, 0, v54
	v_mul_f32_e32 v54, v54, v54
	v_bfe_u32 v55, v54, 16, 1
	v_add3_u32 v54, v54, v55, s96
	global_store_short_d16_hi v[52:53], v54, off offset:96
	v_max_f32_e32 v48, v48, v48
	v_or_b32_e32 v52, 16, v78
	v_max_f32_e32 v48, 0, v48
	v_ashrrev_i32_e32 v53, 31, v52
	v_mul_f32_e32 v48, v48, v48
	v_max_f32_e32 v44, v44, v44
	v_lshlrev_b64 v[52:53], 13, v[52:53]
	v_bfe_u32 v54, v48, 16, 1
	v_max_f32_e32 v44, 0, v44
	v_lshl_add_u64 v[52:53], v[76:77], 0, v[52:53]
	v_add3_u32 v48, v48, v54, s96
	v_mul_f32_e32 v44, v44, v44
	v_max_f32_e32 v40, v40, v40
	global_store_short_d16_hi v[52:53], v48, off
	v_bfe_u32 v48, v44, 16, 1
	v_max_f32_e32 v40, 0, v40
	v_add3_u32 v44, v44, v48, s96
	v_mul_f32_e32 v40, v40, v40
	v_max_f32_e32 v36, v36, v36
	global_store_short_d16_hi v[52:53], v44, off offset:32
	v_bfe_u32 v44, v40, 16, 1
	v_max_f32_e32 v36, 0, v36
	v_add3_u32 v40, v40, v44, s96
	v_mul_f32_e32 v36, v36, v36
	global_store_short_d16_hi v[52:53], v40, off offset:64
	v_bfe_u32 v40, v36, 16, 1
	v_add3_u32 v36, v36, v40, s96
	global_store_short_d16_hi v[52:53], v36, off offset:96
	v_max_f32_e32 v36, v49, v49
	v_or_b32_e32 v52, 17, v78
	v_max_f32_e32 v36, 0, v36
	v_ashrrev_i32_e32 v53, 31, v52
	v_mul_f32_e32 v36, v36, v36
	v_lshlrev_b64 v[52:53], 13, v[52:53]
	v_bfe_u32 v40, v36, 16, 1
	v_lshl_add_u64 v[52:53], v[76:77], 0, v[52:53]
	v_add3_u32 v36, v36, v40, s96
	global_store_short_d16_hi v[52:53], v36, off
	v_max_f32_e32 v36, v45, v45
	v_max_f32_e32 v36, 0, v36
	v_mul_f32_e32 v36, v36, v36
	v_bfe_u32 v40, v36, 16, 1
	v_add3_u32 v36, v36, v40, s96
	global_store_short_d16_hi v[52:53], v36, off offset:32
	v_max_f32_e32 v36, v41, v41
	v_max_f32_e32 v36, 0, v36
	v_mul_f32_e32 v36, v36, v36
	v_bfe_u32 v40, v36, 16, 1
	v_add3_u32 v36, v36, v40, s96
	global_store_short_d16_hi v[52:53], v36, off offset:64
	v_max_f32_e32 v36, v37, v37
	v_max_f32_e32 v36, 0, v36
	v_mul_f32_e32 v36, v36, v36
	v_bfe_u32 v37, v36, 16, 1
	v_add3_u32 v36, v36, v37, s96
	v_max_f32_e32 v40, v50, v50
	global_store_short_d16_hi v[52:53], v36, off offset:96
	v_or_b32_e32 v36, 18, v78
	v_max_f32_e32 v40, 0, v40
	v_ashrrev_i32_e32 v37, 31, v36
	v_mul_f32_e32 v40, v40, v40
	v_lshlrev_b64 v[36:37], 13, v[36:37]
	v_bfe_u32 v41, v40, 16, 1
	v_lshl_add_u64 v[36:37], v[76:77], 0, v[36:37]
	v_add3_u32 v40, v40, v41, s96
	global_store_short_d16_hi v[36:37], v40, off
	v_max_f32_e32 v40, v46, v46
	v_max_f32_e32 v40, 0, v40
	v_mul_f32_e32 v40, v40, v40
	v_bfe_u32 v41, v40, 16, 1
; template <int EPI>
; __device__ void gemm_phase(const u16* __restrict__ A, const u16* __restrict__ Bt, void* __restrict__ Cv,
;                            int N, int K, int ldc, unsigned char* ldsraw, int G) {
;     ...
;     for (int i = 0; i < 4; ++i) {
; #pragma unroll
;       for (int r = 0; r < 4; ++r) {
;         const int m = m0 + wm * 64 + i * 16 + g4 * 4 + r;
;         const int nb = n0 + wn * 64 + l15;
;         if (EPI == EPI_F32) {
;           float* cp = (float*)Cv + (size_t)m * ldc + nb;
; #pragma unroll
;           for (int j = 0; j < 4; ++j) if (nb + j * 16 < N) cp[j * 16] = acc[i][j][r];
;         } else {
;           u16* cp = (u16*)Cv + (size_t)m * ldc + nb;
; #pragma unroll
;           for (int j = 0; j < 4; ++j) {
;             float v = acc[i][j][r];
;             if (EPI == EPI_RELU2) { v = fmaxf(v, 0.f); v = v * v; }
;             if (nb + j * 16 < N) cp[j * 16] = f2bf(v);
;           }
	v_add3_u32 v40, v40, v41, s96
	global_store_short_d16_hi v[36:37], v40, off offset:32
	v_max_f32_e32 v40, v42, v42
	v_max_f32_e32 v40, 0, v40
	v_mul_f32_e32 v40, v40, v40
	v_max_f32_e32 v38, v38, v38
	v_bfe_u32 v41, v40, 16, 1
	v_max_f32_e32 v38, 0, v38
	v_add3_u32 v40, v40, v41, s96
	v_mul_f32_e32 v38, v38, v38
	global_store_short_d16_hi v[36:37], v40, off offset:64
	v_bfe_u32 v40, v38, 16, 1
	v_add3_u32 v38, v38, v40, s96
	global_store_short_d16_hi v[36:37], v38, off offset:96
	v_max_f32_e32 v38, v51, v51
	v_or_b32_e32 v36, 19, v78
	v_max_f32_e32 v38, 0, v38
	v_ashrrev_i32_e32 v37, 31, v36
	v_mul_f32_e32 v38, v38, v38
	v_lshlrev_b64 v[36:37], 13, v[36:37]
	v_bfe_u32 v40, v38, 16, 1
	v_lshl_add_u64 v[36:37], v[76:77], 0, v[36:37]
	v_add3_u32 v38, v38, v40, s96
	global_store_short_d16_hi v[36:37], v38, off
	v_max_f32_e32 v38, v47, v47
	v_max_f32_e32 v38, 0, v38
	v_mul_f32_e32 v38, v38, v38
	v_bfe_u32 v40, v38, 16, 1
	v_add3_u32 v38, v38, v40, s96
	global_store_short_d16_hi v[36:37], v38, off offset:32
	v_max_f32_e32 v38, v43, v43
	v_max_f32_e32 v38, 0, v38
	v_mul_f32_e32 v38, v38, v38
	v_bfe_u32 v40, v38, 16, 1
	v_add3_u32 v38, v38, v40, s96
	global_store_short_d16_hi v[36:37], v38, off offset:64
	v_max_f32_e32 v38, v39, v39
	v_max_f32_e32 v38, 0, v38
	v_mul_f32_e32 v38, v38, v38
	v_bfe_u32 v39, v38, 16, 1
	v_add3_u32 v38, v38, v39, s96
	global_store_short_d16_hi v[36:37], v38, off offset:96
	v_max_f32_e32 v32, v32, v32
	v_or_b32_e32 v36, 32, v78
	v_max_f32_e32 v32, 0, v32
	v_ashrrev_i32_e32 v37, 31, v36
	v_mul_f32_e32 v32, v32, v32
	v_max_f32_e32 v28, v28, v28
	v_lshlrev_b64 v[36:37], 13, v[36:37]
	v_bfe_u32 v38, v32, 16, 1
	v_max_f32_e32 v28, 0, v28
	v_lshl_add_u64 v[36:37], v[76:77], 0, v[36:37]
	v_add3_u32 v32, v32, v38, s96
	v_mul_f32_e32 v28, v28, v28
	v_max_f32_e32 v24, v24, v24
	global_store_short_d16_hi v[36:37], v32, off
	v_bfe_u32 v32, v28, 16, 1
	v_max_f32_e32 v24, 0, v24
	v_add3_u32 v28, v28, v32, s96
	v_mul_f32_e32 v24, v24, v24
	v_max_f32_e32 v20, v20, v20
	global_store_short_d16_hi v[36:37], v28, off offset:32
	v_bfe_u32 v28, v24, 16, 1
	v_max_f32_e32 v20, 0, v20
	v_add3_u32 v24, v24, v28, s96
	v_mul_f32_e32 v20, v20, v20
	global_store_short_d16_hi v[36:37], v24, off offset:64
	v_bfe_u32 v24, v20, 16, 1
	v_add3_u32 v20, v20, v24, s96
	global_store_short_d16_hi v[36:37], v20, off offset:96
	v_max_f32_e32 v20, v33, v33
	v_or_b32_e32 v36, 33, v78
	v_max_f32_e32 v20, 0, v20
	v_ashrrev_i32_e32 v37, 31, v36
	v_mul_f32_e32 v20, v20, v20
	v_lshlrev_b64 v[36:37], 13, v[36:37]
	v_bfe_u32 v24, v20, 16, 1
	v_lshl_add_u64 v[36:37], v[76:77], 0, v[36:37]
	v_add3_u32 v20, v20, v24, s96
	global_store_short_d16_hi v[36:37], v20, off
	v_max_f32_e32 v20, v29, v29
	v_max_f32_e32 v20, 0, v20
	v_mul_f32_e32 v20, v20, v20
	v_bfe_u32 v24, v20, 16, 1
	v_add3_u32 v20, v20, v24, s96
	global_store_short_d16_hi v[36:37], v20, off offset:32
	v_max_f32_e32 v20, v25, v25
	v_max_f32_e32 v20, 0, v20
	v_mul_f32_e32 v20, v20, v20
	v_bfe_u32 v24, v20, 16, 1
	v_add3_u32 v20, v20, v24, s96
	global_store_short_d16_hi v[36:37], v20, off offset:64
	v_max_f32_e32 v20, v21, v21
	v_max_f32_e32 v20, 0, v20
	v_mul_f32_e32 v20, v20, v20
	v_bfe_u32 v21, v20, 16, 1
	v_add3_u32 v20, v20, v21, s96
	v_max_f32_e32 v24, v34, v34
	global_store_short_d16_hi v[36:37], v20, off offset:96
	v_or_b32_e32 v20, 34, v78
	v_max_f32_e32 v24, 0, v24
	v_ashrrev_i32_e32 v21, 31, v20
	v_mul_f32_e32 v24, v24, v24
	v_lshlrev_b64 v[20:21], 13, v[20:21]
	v_bfe_u32 v25, v24, 16, 1
	v_lshl_add_u64 v[20:21], v[76:77], 0, v[20:21]
	v_add3_u32 v24, v24, v25, s96
	global_store_short_d16_hi v[20:21], v24, off
	v_max_f32_e32 v24, v30, v30
	v_max_f32_e32 v24, 0, v24
	v_mul_f32_e32 v24, v24, v24
	v_bfe_u32 v25, v24, 16, 1
	v_add3_u32 v24, v24, v25, s96
	global_store_short_d16_hi v[20:21], v24, off offset:32
	v_max_f32_e32 v24, v26, v26
	v_max_f32_e32 v24, 0, v24
	v_mul_f32_e32 v24, v24, v24
	v_max_f32_e32 v22, v22, v22
	v_bfe_u32 v25, v24, 16, 1
	v_max_f32_e32 v22, 0, v22
	v_add3_u32 v24, v24, v25, s96
	v_mul_f32_e32 v22, v22, v22
	global_store_short_d16_hi v[20:21], v24, off offset:64
	v_bfe_u32 v24, v22, 16, 1
	v_add3_u32 v22, v22, v24, s96
	global_store_short_d16_hi v[20:21], v22, off offset:96
	v_max_f32_e32 v22, v35, v35
	v_or_b32_e32 v20, 35, v78
	v_max_f32_e32 v22, 0, v22
	v_ashrrev_i32_e32 v21, 31, v20
	v_mul_f32_e32 v22, v22, v22
; template <int EPI>
; __device__ void gemm_phase(const u16* __restrict__ A, const u16* __restrict__ Bt, void* __restrict__ Cv,
;                            int N, int K, int ldc, unsigned char* ldsraw, int G) {
;     ...
;     for (int i = 0; i < 4; ++i) {
; #pragma unroll
;       for (int r = 0; r < 4; ++r) {
;         const int m = m0 + wm * 64 + i * 16 + g4 * 4 + r;
;         const int nb = n0 + wn * 64 + l15;
;         if (EPI == EPI_F32) {
;           float* cp = (float*)Cv + (size_t)m * ldc + nb;
; #pragma unroll
;           for (int j = 0; j < 4; ++j) if (nb + j * 16 < N) cp[j * 16] = acc[i][j][r];
;         } else {
;           u16* cp = (u16*)Cv + (size_t)m * ldc + nb;
; #pragma unroll
;           for (int j = 0; j < 4; ++j) {
;             float v = acc[i][j][r];
;             if (EPI == EPI_RELU2) { v = fmaxf(v, 0.f); v = v * v; }
;             if (nb + j * 16 < N) cp[j * 16] = f2bf(v);
;           }
;         }
;       }
;       __builtin_amdgcn_sched_barrier(0);
;     }
;   }
	v_lshlrev_b64 v[20:21], 13, v[20:21]
	v_bfe_u32 v24, v22, 16, 1
	v_lshl_add_u64 v[20:21], v[76:77], 0, v[20:21]
	v_add3_u32 v22, v22, v24, s96
	global_store_short_d16_hi v[20:21], v22, off
	v_max_f32_e32 v22, v31, v31
	v_max_f32_e32 v22, 0, v22
	v_mul_f32_e32 v22, v22, v22
	v_bfe_u32 v24, v22, 16, 1
	v_add3_u32 v22, v22, v24, s96
	global_store_short_d16_hi v[20:21], v22, off offset:32
	v_max_f32_e32 v22, v27, v27
	v_max_f32_e32 v22, 0, v22
	v_mul_f32_e32 v22, v22, v22
	v_bfe_u32 v24, v22, 16, 1
	v_add3_u32 v22, v22, v24, s96
	global_store_short_d16_hi v[20:21], v22, off offset:64
	v_max_f32_e32 v22, v23, v23
	v_max_f32_e32 v22, 0, v22
	v_mul_f32_e32 v22, v22, v22
	v_bfe_u32 v23, v22, 16, 1
	v_add3_u32 v22, v22, v23, s96
	global_store_short_d16_hi v[20:21], v22, off offset:96
	v_max_f32_e32 v16, v16, v16
	v_or_b32_e32 v20, 48, v78
	v_max_f32_e32 v16, 0, v16
	v_ashrrev_i32_e32 v21, 31, v20
	v_mul_f32_e32 v16, v16, v16
	v_max_f32_e32 v12, v12, v12
	v_lshlrev_b64 v[20:21], 13, v[20:21]
	v_bfe_u32 v22, v16, 16, 1
	v_max_f32_e32 v12, 0, v12
	v_lshl_add_u64 v[20:21], v[76:77], 0, v[20:21]
	v_add3_u32 v16, v16, v22, s96
	v_mul_f32_e32 v12, v12, v12
	v_max_f32_e32 v8, v8, v8
	global_store_short_d16_hi v[20:21], v16, off
	v_bfe_u32 v16, v12, 16, 1
	v_max_f32_e32 v8, 0, v8
	v_add3_u32 v12, v12, v16, s96
	v_mul_f32_e32 v8, v8, v8
	v_max_f32_e32 v2, v2, v2
	global_store_short_d16_hi v[20:21], v12, off offset:32
	v_bfe_u32 v12, v8, 16, 1
	v_max_f32_e32 v2, 0, v2
	v_add3_u32 v8, v8, v12, s96
	v_mul_f32_e32 v2, v2, v2
	global_store_short_d16_hi v[20:21], v8, off offset:64
	v_bfe_u32 v8, v2, 16, 1
	v_add3_u32 v2, v2, v8, s96
	global_store_short_d16_hi v[20:21], v2, off offset:96
	v_max_f32_e32 v2, v17, v17
	v_or_b32_e32 v20, 49, v78
	v_max_f32_e32 v2, 0, v2
	v_ashrrev_i32_e32 v21, 31, v20
	v_mul_f32_e32 v2, v2, v2
	v_lshlrev_b64 v[20:21], 13, v[20:21]
	v_bfe_u32 v8, v2, 16, 1
	v_lshl_add_u64 v[20:21], v[76:77], 0, v[20:21]
	v_add3_u32 v2, v2, v8, s96
	global_store_short_d16_hi v[20:21], v2, off
	v_max_f32_e32 v2, v13, v13
	v_max_f32_e32 v2, 0, v2
	v_mul_f32_e32 v2, v2, v2
	v_bfe_u32 v8, v2, 16, 1
	v_add3_u32 v2, v2, v8, s96
	global_store_short_d16_hi v[20:21], v2, off offset:32
	v_max_f32_e32 v2, v9, v9
	v_max_f32_e32 v2, 0, v2
	v_mul_f32_e32 v2, v2, v2
	v_bfe_u32 v8, v2, 16, 1
	v_add3_u32 v2, v2, v8, s96
	global_store_short_d16_hi v[20:21], v2, off offset:64
	v_max_f32_e32 v2, v3, v3
	v_max_f32_e32 v2, 0, v2
	v_mul_f32_e32 v2, v2, v2
	v_bfe_u32 v3, v2, 16, 1
	v_add3_u32 v2, v2, v3, s96
	v_max_f32_e32 v8, v18, v18
	global_store_short_d16_hi v[20:21], v2, off offset:96
	v_or_b32_e32 v2, 50, v78
	v_max_f32_e32 v8, 0, v8
	v_ashrrev_i32_e32 v3, 31, v2
	v_mul_f32_e32 v8, v8, v8
	v_lshlrev_b64 v[2:3], 13, v[2:3]
	v_bfe_u32 v9, v8, 16, 1
	v_lshl_add_u64 v[2:3], v[76:77], 0, v[2:3]
	v_add3_u32 v8, v8, v9, s96
	global_store_short_d16_hi v[2:3], v8, off
	v_max_f32_e32 v8, v14, v14
	v_max_f32_e32 v8, 0, v8
	v_mul_f32_e32 v8, v8, v8
	v_bfe_u32 v9, v8, 16, 1
	v_add3_u32 v8, v8, v9, s96
	global_store_short_d16_hi v[2:3], v8, off offset:32
	v_max_f32_e32 v8, v10, v10
	v_max_f32_e32 v8, 0, v8
	v_mul_f32_e32 v8, v8, v8
	v_max_f32_e32 v4, v4, v4
	v_bfe_u32 v9, v8, 16, 1
	v_max_f32_e32 v4, 0, v4
	v_add3_u32 v8, v8, v9, s96
	v_mul_f32_e32 v4, v4, v4
	global_store_short_d16_hi v[2:3], v8, off offset:64
	v_bfe_u32 v8, v4, 16, 1
	v_add3_u32 v4, v4, v8, s96
	global_store_short_d16_hi v[2:3], v4, off offset:96
	v_max_f32_e32 v4, v19, v19
	v_or_b32_e32 v2, 51, v78
	v_max_f32_e32 v4, 0, v4
	v_ashrrev_i32_e32 v3, 31, v2
	v_mul_f32_e32 v4, v4, v4
	v_lshlrev_b64 v[2:3], 13, v[2:3]
	v_bfe_u32 v8, v4, 16, 1
	v_lshl_add_u64 v[2:3], v[76:77], 0, v[2:3]
	v_add3_u32 v4, v4, v8, s96
	global_store_short_d16_hi v[2:3], v4, off
	v_max_f32_e32 v4, v15, v15
	v_max_f32_e32 v4, 0, v4
	v_mul_f32_e32 v4, v4, v4
	v_bfe_u32 v8, v4, 16, 1
	v_add3_u32 v4, v4, v8, s96
	global_store_short_d16_hi v[2:3], v4, off offset:32
	v_max_f32_e32 v4, v11, v11
	v_max_f32_e32 v4, 0, v4
	v_mul_f32_e32 v4, v4, v4
	v_bfe_u32 v8, v4, 16, 1
	v_add3_u32 v4, v4, v8, s96
	global_store_short_d16_hi v[2:3], v4, off offset:64
	v_max_f32_e32 v4, v5, v5
	v_max_f32_e32 v4, 0, v4
	v_mul_f32_e32 v4, v4, v4
	v_bfe_u32 v5, v4, 16, 1
	v_add3_u32 v4, v4, v5, s96
	global_store_short_d16_hi v[2:3], v4, off offset:96
	s_add_i32 s0, s0, s33
	s_cmpk_gt_i32 s0, 0x7ff
	s_cbranch_scc0 .LBB0_154

; __device__ __forceinline__ void lds_barrier() { asm volatile("s_waitcnt lgkmcnt(0)\n\ts_barrier" ::: "memory"); }
; template <int EPI>
; __device__ void gemm_phase(const u16* __restrict__ A, const u16* __restrict__ Bt, void* __restrict__ Cv,
;                            int N, int K, int ldc, unsigned char* ldsraw, int G) {
;     ...
;     GLDS(0, 0);
;     GLDS(1, 1);
;     if (__builtin_amdgcn_readfirstlane(tid) >= 256) __builtin_amdgcn_s_setprio(1);
;     int st = 0;
;     for (int kt = 0; kt < nk; ++kt) {
;       asm volatile("s_waitcnt vmcnt(6)" ::: "memory");
;       lds_barrier();
;       const int st2 = (st >= 1) ? st - 1 : 2;
;       GLDS(st2, kt + 2);
;       const u16* Asx = As + st * STG;
;       const u16* Bsx = Asx + GBM * GLD;
; #pragma unroll
;       for (int ks = 0; ks < 2; ++ks) {
;         const int fsw = ((ks * 4 + g4) ^ fx) * 8;
;         bf16x8 bfr[4];
; #pragma unroll
;         for (int jx = 0; jx < 4; ++jx) bfr[jx] = *(const bf16x8*)(Bsx + (wn * 64 + jx * 16 + l15) * GLD + fsw);
; #pragma unroll
;         for (int ix = 0; ix < 4; ++ix) {
;           const bf16x8 af = *(const bf16x8*)(Asx + (wm * 64 + ix * 16 + l15) * GLD + fsw);
; #pragma unroll
;           for (int jx = 0; jx < 4; ++jx)
;             acc[ix][jx] = __builtin_amdgcn_mfma_f32_16x16x32_bf16(af, bfr[jx], acc[ix][jx], 0, 0, 0);
;         }
;       }
;       st = (st == 2) ? 0 : st + 1;
;     }
.LBB0_176:
	s_mul_i32 s8, s5, 0xc000
	s_min_u32 s7, s6, 13
	s_add_i32 s9, s8, 0xffff4000
	s_cmp_gt_i32 s5, 0
	s_waitcnt vmcnt(6)
	s_cselect_b32 s9, s9, 0x18000
	s_lshl_b32 s98, s7, 7
	s_add_i32 s98, s98, 0x100
	s_add_i32 s7, s8, 0x100
	s_add_i32 s8, s9, s4
	s_add_i32 s9, s8, 0x2000
	s_add_i32 s11, s8, 0x4000
	s_add_i32 s12, s8, 0x6000
	s_add_i32 s13, s8, 0x8000
	s_add_i32 s14, s8, 0xa000
	v_lshl_add_u64 v[236:237], v[76:77], 0, s[98:99]
	v_lshl_add_u64 v[238:239], v[80:81], 0, s[98:99]
	v_lshl_add_u64 v[240:241], v[82:83], 0, s[98:99]
	v_lshl_add_u64 v[242:243], v[84:85], 0, s[98:99]
	v_lshl_add_u64 v[244:245], v[78:79], 0, s[98:99]
	v_lshl_add_u64 v[246:247], v[86:87], 0, s[98:99]
	v_lshl_add_u32 v109, v104, 1, s7
	v_add3_u32 v130, v109, v105, v106
	v_add3_u32 v109, v109, v107, v106
	s_waitcnt lgkmcnt(0)
	s_barrier
	s_mov_b32 s15, m0
	ds_read_b128 v[110:113], v109
	ds_read_b128 v[114:117], v130 offset:32768
	ds_read_b128 v[118:121], v130 offset:34816
	ds_read_b128 v[122:125], v109 offset:2048
	ds_read_b128 v[126:129], v130 offset:36864
	ds_read_b128 v[130:133], v130 offset:38912
	s_waitcnt lgkmcnt(4)
	v_mfma_f32_16x16x32_bf16 v[64:67], v[110:113], v[114:117], v[64:67]
	s_waitcnt lgkmcnt(3)
	v_mfma_f32_16x16x32_bf16 v[60:63], v[110:113], v[118:121], v[60:63]
	s_waitcnt lgkmcnt(1)
	v_mfma_f32_16x16x32_bf16 v[56:59], v[110:113], v[126:129], v[56:59]
	s_waitcnt lgkmcnt(0)
	s_mov_b32 m0, s8
	v_mfma_f32_16x16x32_bf16 v[52:55], v[110:113], v[130:133], v[52:55]
	global_load_lds_dwordx4 v[236:237], off
	v_mfma_f32_16x16x32_bf16 v[48:51], v[122:125], v[114:117], v[48:51]
	v_mfma_f32_16x16x32_bf16 v[44:47], v[122:125], v[118:121], v[44:47]
	v_mfma_f32_16x16x32_bf16 v[40:43], v[122:125], v[126:129], v[40:43]
	v_mfma_f32_16x16x32_bf16 v[36:39], v[122:125], v[130:133], v[36:39]
	ds_read_b128 v[110:113], v109 offset:4096
	ds_read_b128 v[122:125], v109 offset:6144
	v_lshl_add_u32 v109, v108, 1, s7
	v_add3_u32 v134, v109, v105, v106
	v_add3_u32 v109, v109, v107, v106
	s_waitcnt lgkmcnt(1)
	s_mov_b32 m0, s9
	v_mfma_f32_16x16x32_bf16 v[32:35], v[110:113], v[114:117], v[32:35]
	global_load_lds_dwordx4 v[238:239], off
	s_add_i32 s7, s5, 1
	s_cmp_lg_u32 s5, 2
	s_cselect_b32 s5, s7, 0
	v_mfma_f32_16x16x32_bf16 v[28:31], v[110:113], v[118:121], v[28:31]
	s_add_i32 s6, s6, 1
	s_cmp_eq_u32 s6, 16
	v_mfma_f32_16x16x32_bf16 v[24:27], v[110:113], v[126:129], v[24:27]
	v_mfma_f32_16x16x32_bf16 v[20:23], v[110:113], v[130:133], v[20:23]
	ds_read_b128 v[110:113], v109
	s_waitcnt lgkmcnt(1)
	v_mfma_f32_16x16x32_bf16 v[16:19], v[122:125], v[114:117], v[16:19]
	s_mov_b32 m0, s11
	v_mfma_f32_16x16x32_bf16 v[12:15], v[122:125], v[118:121], v[12:15]
	global_load_lds_dwordx4 v[240:241], off
	v_mfma_f32_16x16x32_bf16 v[8:11], v[122:125], v[126:129], v[8:11]
	v_mfma_f32_16x16x32_bf16 v[2:5], v[122:125], v[130:133], v[2:5]
	ds_read_b128 v[114:117], v134 offset:32768
	ds_read_b128 v[118:121], v134 offset:34816
	ds_read_b128 v[122:125], v109 offset:2048
	ds_read_b128 v[126:129], v134 offset:36864
	ds_read_b128 v[130:133], v134 offset:38912
	s_waitcnt lgkmcnt(4)
	v_mfma_f32_16x16x32_bf16 v[64:67], v[110:113], v[114:117], v[64:67]
	s_waitcnt lgkmcnt(3)
	v_mfma_f32_16x16x32_bf16 v[60:63], v[110:113], v[118:121], v[60:63]
	s_waitcnt lgkmcnt(1)
	s_mov_b32 m0, s12
	v_mfma_f32_16x16x32_bf16 v[56:59], v[110:113], v[126:129], v[56:59]
	global_load_lds_dwordx4 v[242:243], off
	s_waitcnt lgkmcnt(0)
	v_mfma_f32_16x16x32_bf16 v[52:55], v[110:113], v[130:133], v[52:55]
	v_mfma_f32_16x16x32_bf16 v[48:51], v[122:125], v[114:117], v[48:51]
	v_mfma_f32_16x16x32_bf16 v[44:47], v[122:125], v[118:121], v[44:47]
	v_mfma_f32_16x16x32_bf16 v[40:43], v[122:125], v[126:129], v[40:43]
	s_mov_b32 m0, s13
	v_mfma_f32_16x16x32_bf16 v[36:39], v[122:125], v[130:133], v[36:39]
	global_load_lds_dwordx4 v[244:245], off
	ds_read_b128 v[110:113], v109 offset:4096
	ds_read_b128 v[122:125], v109 offset:6144
	s_waitcnt lgkmcnt(1)
	v_mfma_f32_16x16x32_bf16 v[32:35], v[110:113], v[114:117], v[32:35]
	v_mfma_f32_16x16x32_bf16 v[28:31], v[110:113], v[118:121], v[28:31]
	v_mfma_f32_16x16x32_bf16 v[24:27], v[110:113], v[126:129], v[24:27]
	v_mfma_f32_16x16x32_bf16 v[20:23], v[110:113], v[130:133], v[20:23]
	s_waitcnt lgkmcnt(0)
	s_mov_b32 m0, s14
	v_mfma_f32_16x16x32_bf16 v[16:19], v[122:125], v[114:117], v[16:19]
	global_load_lds_dwordx4 v[246:247], off
	s_mov_b32 m0, s15
	v_mfma_f32_16x16x32_bf16 v[12:15], v[122:125], v[118:121], v[12:15]
	v_mfma_f32_16x16x32_bf16 v[8:11], v[122:125], v[126:129], v[8:11]
	v_mfma_f32_16x16x32_bf16 v[2:5], v[122:125], v[130:133], v[2:5]
	s_cbranch_scc0 .LBB0_176
	s_setprio 0
	s_waitcnt vmcnt(0)
	v_add_u32_e32 v78, s0, v0
	v_or_b32_e32 v82, s1, v75
	s_waitcnt lgkmcnt(0)
	s_barrier
	v_ashrrev_i32_e32 v83, 31, v82
	v_ashrrev_i32_e32 v79, 31, v78
	v_lshl_add_u64 v[76:77], v[82:83], 1, s[76:77]
	v_lshlrev_b64 v[80:81], 11, v[78:79]
	s_movk_i32 s0, 0x400
	v_lshl_add_u64 v[80:81], v[76:77], 0, v[80:81]
	v_cmp_gt_i32_e32 vcc, s0, v82
	s_and_saveexec_b64 s[0:1], vcc
	s_cbranch_execz .LBB0_179
	v_bfe_u32 v79, v64, 16, 1
	v_add3_u32 v64, v64, v79, s96
	global_store_short_d16_hi v[80:81], v64, off

; __device__ __forceinline__ void lds_barrier() { asm volatile("s_waitcnt lgkmcnt(0)\n\ts_barrier" ::: "memory"); }
; template <int EPI>
; __device__ void gemm_phase(const u16* __restrict__ A, const u16* __restrict__ Bt, void* __restrict__ Cv,
;                            int N, int K, int ldc, unsigned char* ldsraw, int G) {
;     ...
;     GLDS(0, 0);
;     GLDS(1, 1);
;     if (__builtin_amdgcn_readfirstlane(tid) >= 256) __builtin_amdgcn_s_setprio(1);
;     int st = 0;
;     for (int kt = 0; kt < nk; ++kt) {
;       asm volatile("s_waitcnt vmcnt(6)" ::: "memory");
;       lds_barrier();
;       const int st2 = (st >= 1) ? st - 1 : 2;
;       GLDS(st2, kt + 2);
;       const u16* Asx = As + st * STG;
;       const u16* Bsx = Asx + GBM * GLD;
; #pragma unroll
;       for (int ks = 0; ks < 2; ++ks) {
;         const int fsw = ((ks * 4 + g4) ^ fx) * 8;
;         bf16x8 bfr[4];
; #pragma unroll
;         for (int jx = 0; jx < 4; ++jx) bfr[jx] = *(const bf16x8*)(Bsx + (wn * 64 + jx * 16 + l15) * GLD + fsw);
; #pragma unroll
;         for (int ix = 0; ix < 4; ++ix) {
;           const bf16x8 af = *(const bf16x8*)(Asx + (wm * 64 + ix * 16 + l15) * GLD + fsw);
; #pragma unroll
;           for (int jx = 0; jx < 4; ++jx)
;             acc[ix][jx] = __builtin_amdgcn_mfma_f32_16x16x32_bf16(af, bfr[jx], acc[ix][jx], 0, 0, 0);
;         }
;       }
;       st = (st == 2) ? 0 : st + 1;
;     }
.LBB0_830:
	s_mul_i32 s7, s4, 0xc000
	s_min_u32 s6, s5, 13
	s_add_i32 s8, s7, 0xffff4000
	s_cmp_gt_i32 s4, 0
	s_waitcnt vmcnt(6)
	s_cselect_b32 s8, s8, 0x18000
	s_lshl_b32 s98, s6, 7
	s_add_i32 s98, s98, 0x100
	s_add_i32 s6, s7, 0x100
	s_add_i32 s7, s8, s3
	s_add_i32 s8, s7, 0x2000
	s_add_i32 s9, s7, 0x4000
	s_add_i32 s10, s7, 0x6000
	s_add_i32 s11, s7, 0x8000
	s_add_i32 s12, s7, 0xa000
	v_lshl_add_u64 v[236:237], v[76:77], 0, s[98:99]
	v_lshl_add_u64 v[238:239], v[80:81], 0, s[98:99]
	v_lshl_add_u64 v[240:241], v[82:83], 0, s[98:99]
	v_lshl_add_u64 v[242:243], v[84:85], 0, s[98:99]
	v_lshl_add_u64 v[244:245], v[78:79], 0, s[98:99]
	v_lshl_add_u64 v[246:247], v[86:87], 0, s[98:99]
	v_lshl_add_u32 v109, v104, 1, s6
	v_add3_u32 v130, v109, v105, v106
	v_add3_u32 v109, v109, v107, v106
	s_waitcnt lgkmcnt(0)
	s_barrier
	s_mov_b32 s13, m0
	ds_read_b128 v[110:113], v109
	ds_read_b128 v[114:117], v130 offset:32768
	ds_read_b128 v[118:121], v130 offset:34816
	ds_read_b128 v[122:125], v109 offset:2048
	ds_read_b128 v[126:129], v130 offset:36864
	ds_read_b128 v[130:133], v130 offset:38912
	s_waitcnt lgkmcnt(4)
	v_mfma_f32_16x16x32_bf16 v[64:67], v[110:113], v[114:117], v[64:67]
	s_waitcnt lgkmcnt(3)
	v_mfma_f32_16x16x32_bf16 v[60:63], v[110:113], v[118:121], v[60:63]
	s_waitcnt lgkmcnt(1)
	v_mfma_f32_16x16x32_bf16 v[56:59], v[110:113], v[126:129], v[56:59]
	s_waitcnt lgkmcnt(0)
	s_mov_b32 m0, s7
	v_mfma_f32_16x16x32_bf16 v[52:55], v[110:113], v[130:133], v[52:55]
	global_load_lds_dwordx4 v[236:237], off
	v_mfma_f32_16x16x32_bf16 v[48:51], v[122:125], v[114:117], v[48:51]
	v_mfma_f32_16x16x32_bf16 v[44:47], v[122:125], v[118:121], v[44:47]
	v_mfma_f32_16x16x32_bf16 v[40:43], v[122:125], v[126:129], v[40:43]
	v_mfma_f32_16x16x32_bf16 v[36:39], v[122:125], v[130:133], v[36:39]
	ds_read_b128 v[110:113], v109 offset:4096
	ds_read_b128 v[122:125], v109 offset:6144
	v_lshl_add_u32 v109, v108, 1, s6
	v_add3_u32 v134, v109, v105, v106
	v_add3_u32 v109, v109, v107, v106
	s_waitcnt lgkmcnt(1)
	s_mov_b32 m0, s8
	v_mfma_f32_16x16x32_bf16 v[32:35], v[110:113], v[114:117], v[32:35]
	global_load_lds_dwordx4 v[238:239], off
	s_add_i32 s6, s4, 1
	s_cmp_lg_u32 s4, 2
	s_cselect_b32 s4, s6, 0
	v_mfma_f32_16x16x32_bf16 v[28:31], v[110:113], v[118:121], v[28:31]
	s_add_i32 s5, s5, 1
	s_cmp_eq_u32 s5, 16
	v_mfma_f32_16x16x32_bf16 v[24:27], v[110:113], v[126:129], v[24:27]
	v_mfma_f32_16x16x32_bf16 v[20:23], v[110:113], v[130:133], v[20:23]
	ds_read_b128 v[110:113], v109
	s_waitcnt lgkmcnt(1)
	v_mfma_f32_16x16x32_bf16 v[16:19], v[122:125], v[114:117], v[16:19]
	s_mov_b32 m0, s9
	v_mfma_f32_16x16x32_bf16 v[12:15], v[122:125], v[118:121], v[12:15]
	global_load_lds_dwordx4 v[240:241], off
	v_mfma_f32_16x16x32_bf16 v[8:11], v[122:125], v[126:129], v[8:11]
	v_mfma_f32_16x16x32_bf16 v[2:5], v[122:125], v[130:133], v[2:5]
	ds_read_b128 v[114:117], v134 offset:32768
	ds_read_b128 v[118:121], v134 offset:34816
	ds_read_b128 v[122:125], v109 offset:2048
	ds_read_b128 v[126:129], v134 offset:36864
	ds_read_b128 v[130:133], v134 offset:38912
	s_waitcnt lgkmcnt(4)
	v_mfma_f32_16x16x32_bf16 v[64:67], v[110:113], v[114:117], v[64:67]
	s_waitcnt lgkmcnt(3)
	v_mfma_f32_16x16x32_bf16 v[60:63], v[110:113], v[118:121], v[60:63]
	s_waitcnt lgkmcnt(1)
	s_mov_b32 m0, s10
	v_mfma_f32_16x16x32_bf16 v[56:59], v[110:113], v[126:129], v[56:59]
	global_load_lds_dwordx4 v[242:243], off
	s_waitcnt lgkmcnt(0)
	v_mfma_f32_16x16x32_bf16 v[52:55], v[110:113], v[130:133], v[52:55]
	v_mfma_f32_16x16x32_bf16 v[48:51], v[122:125], v[114:117], v[48:51]
	v_mfma_f32_16x16x32_bf16 v[44:47], v[122:125], v[118:121], v[44:47]
	v_mfma_f32_16x16x32_bf16 v[40:43], v[122:125], v[126:129], v[40:43]
	s_mov_b32 m0, s11
	v_mfma_f32_16x16x32_bf16 v[36:39], v[122:125], v[130:133], v[36:39]
	global_load_lds_dwordx4 v[244:245], off
	ds_read_b128 v[110:113], v109 offset:4096
	ds_read_b128 v[122:125], v109 offset:6144
	s_waitcnt lgkmcnt(1)
	v_mfma_f32_16x16x32_bf16 v[32:35], v[110:113], v[114:117], v[32:35]
	v_mfma_f32_16x16x32_bf16 v[28:31], v[110:113], v[118:121], v[28:31]
	v_mfma_f32_16x16x32_bf16 v[24:27], v[110:113], v[126:129], v[24:27]
	v_mfma_f32_16x16x32_bf16 v[20:23], v[110:113], v[130:133], v[20:23]
	s_waitcnt lgkmcnt(0)
	s_mov_b32 m0, s12
	v_mfma_f32_16x16x32_bf16 v[16:19], v[122:125], v[114:117], v[16:19]
	global_load_lds_dwordx4 v[246:247], off
	s_mov_b32 m0, s13
	v_mfma_f32_16x16x32_bf16 v[12:15], v[122:125], v[118:121], v[12:15]
	v_mfma_f32_16x16x32_bf16 v[8:11], v[122:125], v[126:129], v[8:11]
	v_mfma_f32_16x16x32_bf16 v[2:5], v[122:125], v[130:133], v[2:5]
	s_cbranch_scc0 .LBB0_830
	s_setprio 0
	v_or_b32_e32 v80, s1, v75
	v_ashrrev_i32_e32 v81, 31, v80
	s_waitcnt vmcnt(0)
	v_add_u32_e32 v82, s0, v0
	v_lshl_add_u64 v[76:77], v[80:81], 1, s[76:77]
	s_waitcnt lgkmcnt(0)
	s_barrier
	v_mad_i64_i32 v[78:79], s[0:1], v82, s83, v[76:77]
	s_movk_i32 s0, 0xc90
	s_nop 0
	v_cmp_gt_i32_e32 vcc, s0, v80
	s_and_saveexec_b64 s[0:1], vcc
	s_cbranch_execz .LBB0_833
	v_bfe_u32 v81, v64, 16, 1
	v_add3_u32 v64, v64, v81, s96
	global_store_short_d16_hi v[78:79], v64, off
